# v26 + w_in ssq-out blocks (lora slabs): 32 more symmetric ds_bpermute reductions done with v_permlane16/32_swap
# speedup vs baseline: 1.0053x; 1.0053x over previous
;     __device__ __forceinline__ void operator()(const f32x4 (&acc)[2][2][4][2], const Unit& u, int wr, int wc, int fr, int fq) const {
;     ...
;                     if (sq) { float s = (v0[0] * v0[0] + v0[1] * v0[1]) + (v0[2] * v0[2] + v0[3] * v0[3]) + (v1[0] * v1[0] + v1[1] * v1[1]) + (v1[2] * v1[2] + v1[3] * v1[3]);
;                         s += __shfl_xor(s, 16); s += __shfl_xor(s, 32); if (fq == 0) sq[(size_t)row * sqp] = s; }
.LBB0_361:
	v_mul_f32_e32 v0, v127, v127
	v_mul_f32_e32 v166, v129, v129
	v_fmac_f32_e32 v0, v126, v126
	v_fmac_f32_e32 v166, v128, v128
	v_add_f32_e32 v0, v0, v166
	v_mul_f32_e32 v166, v123, v123
	v_fmac_f32_e32 v166, v122, v122
	v_add_f32_e32 v0, v0, v166
	v_mul_f32_e32 v166, v125, v125
	v_fmac_f32_e32 v166, v124, v124
	v_and_b32_e32 v167, 64, v241
	v_add_f32_e32 v0, v166, v0
	v_xor_b32_e32 v166, 16, v241
	v_add_u32_e32 v167, 64, v167
	v_cmp_lt_i32_e32 vcc, v166, v167
	s_nop 1
	v_cndmask_b32_e32 v166, v241, v166, vcc
	v_lshlrev_b32_e32 v166, 2, v166
	v_mov_b32_e32 v166, v0
	s_nop 1
	v_permlane16_swap_b32_e32 v0, v166
	s_waitcnt lgkmcnt(0)
	v_add_f32_e32 v0, v0, v166
	v_xor_b32_e32 v166, 32, v241
	v_cmp_lt_i32_e32 vcc, v166, v167
	s_nop 1
	v_cndmask_b32_e32 v166, v241, v166, vcc
	v_lshlrev_b32_e32 v166, 2, v166
	v_mov_b32_e32 v166, v0
	s_nop 1
	v_permlane32_swap_b32_e32 v0, v166
	s_and_saveexec_b64 s[30:31], s[46:47]
	s_cbranch_execz .LBB0_363
	s_waitcnt lgkmcnt(0)
	v_add_f32_e32 v0, v0, v166
	v_mul_lo_u32 v168, s29, v156
	v_mul_lo_u32 v169, s28, v157
	v_mad_u64_u32 v[166:167], s[6:7], s28, v156, 0
	v_add3_u32 v167, v167, v169, v168
	v_lshl_add_u64 v[166:167], v[166:167], 2, s[0:1]
	global_store_dword v[166:167], v0, off

;     __device__ __forceinline__ void operator()(const f32x4 (&acc)[2][2][4][2], const Unit& u, int wr, int wc, int fr, int fq) const {
;     ...
;                     if (sq) { float s = (v0[0] * v0[0] + v0[1] * v0[1]) + (v0[2] * v0[2] + v0[3] * v0[3]) + (v1[0] * v1[0] + v1[1] * v1[1]) + (v1[2] * v1[2] + v1[3] * v1[3]);
;                         s += __shfl_xor(s, 16); s += __shfl_xor(s, 32); if (fq == 0) sq[(size_t)row * sqp] = s; }
.LBB0_368:
	v_cndmask_b32_e64 v124, 0, 1, s[54:55]
	v_cmp_ne_u32_e64 s[52:53], 1, v124
	s_andn2_b64 vcc, exec, s[54:55]
	s_mov_b32 s55, 0x800000
	s_cbranch_vccnz .LBB0_372
	v_mul_f32_e32 v124, v119, v119
	v_mul_f32_e32 v125, v121, v121
	v_fmac_f32_e32 v124, v118, v118
	v_fmac_f32_e32 v125, v120, v120
	v_add_f32_e32 v124, v124, v125
	v_mul_f32_e32 v125, v115, v115
	v_fmac_f32_e32 v125, v114, v114
	v_add_f32_e32 v124, v124, v125
	v_mul_f32_e32 v125, v117, v117
	v_fmac_f32_e32 v125, v116, v116
	v_and_b32_e32 v126, 64, v241
	v_add_f32_e32 v124, v125, v124
	v_xor_b32_e32 v125, 16, v241
	v_add_u32_e32 v126, 64, v126
	v_cmp_lt_i32_e32 vcc, v125, v126
	s_nop 1
	v_cndmask_b32_e32 v125, v241, v125, vcc
	v_lshlrev_b32_e32 v125, 2, v125
	v_mov_b32_e32 v125, v124
	s_nop 1
	v_permlane16_swap_b32_e32 v124, v125
	s_waitcnt lgkmcnt(0)
	v_add_f32_e32 v124, v124, v125
	v_xor_b32_e32 v125, 32, v241
	v_cmp_lt_i32_e32 vcc, v125, v126
	s_nop 1
	v_cndmask_b32_e32 v125, v241, v125, vcc
	v_lshlrev_b32_e32 v125, 2, v125
	v_mov_b32_e32 v125, v124
	s_nop 1
	v_permlane32_swap_b32_e32 v124, v125
	s_and_saveexec_b64 s[34:35], s[46:47]
	s_cbranch_execz .LBB0_371
	s_waitcnt lgkmcnt(0)
	v_add_f32_e32 v126, v124, v125
	v_ashrrev_i32_e32 v124, 31, v154
	v_mul_lo_u32 v127, s29, v154
	v_mul_lo_u32 v128, s28, v124
	v_mad_u64_u32 v[124:125], s[6:7], s28, v154, 0
	v_add3_u32 v125, v125, v128, v127
	v_lshl_add_u64 v[124:125], v[124:125], 2, s[0:1]
	global_store_dword v[124:125], v126, off

;     __device__ __forceinline__ void operator()(const f32x4 (&acc)[2][2][4][2], const Unit& u, int wr, int wc, int fr, int fq) const {
;     ...
;                     if (sq) { float s = (v0[0] * v0[0] + v0[1] * v0[1]) + (v0[2] * v0[2] + v0[3] * v0[3]) + (v1[0] * v1[0] + v1[1] * v1[1]) + (v1[2] * v1[2] + v1[3] * v1[3]);
;                         s += __shfl_xor(s, 16); s += __shfl_xor(s, 32); if (fq == 0) sq[(size_t)row * sqp] = s; }
.LBB0_377:
	v_mul_f32_e32 v116, v111, v111
	v_mul_f32_e32 v117, v113, v113
	v_fmac_f32_e32 v116, v110, v110
	v_fmac_f32_e32 v117, v112, v112
	v_add_f32_e32 v116, v116, v117
	v_mul_f32_e32 v117, v107, v107
	v_fmac_f32_e32 v117, v106, v106
	v_add_f32_e32 v116, v116, v117
	v_mul_f32_e32 v117, v109, v109
	v_fmac_f32_e32 v117, v108, v108
	v_and_b32_e32 v118, 64, v241
	v_add_f32_e32 v116, v117, v116
	v_xor_b32_e32 v117, 16, v241
	v_add_u32_e32 v118, 64, v118
	v_cmp_lt_i32_e32 vcc, v117, v118
	s_nop 1
	v_cndmask_b32_e32 v117, v241, v117, vcc
	v_lshlrev_b32_e32 v117, 2, v117
	v_mov_b32_e32 v117, v116
	s_nop 1
	v_permlane16_swap_b32_e32 v116, v117
	s_waitcnt lgkmcnt(0)
	v_add_f32_e32 v116, v116, v117
	v_xor_b32_e32 v117, 32, v241
	v_cmp_lt_i32_e32 vcc, v117, v118
	s_nop 1
	v_cndmask_b32_e32 v117, v241, v117, vcc
	v_lshlrev_b32_e32 v117, 2, v117
	v_mov_b32_e32 v117, v116
	s_nop 1
	v_permlane32_swap_b32_e32 v116, v117
	s_and_saveexec_b64 s[34:35], s[46:47]
	s_cbranch_execz .LBB0_379
	s_waitcnt lgkmcnt(0)
	v_add_f32_e32 v118, v116, v117
	v_ashrrev_i32_e32 v116, 31, v152
	v_mul_lo_u32 v119, s29, v152
	v_mul_lo_u32 v120, s28, v116
	v_mad_u64_u32 v[116:117], s[6:7], s28, v152, 0
	v_add3_u32 v117, v117, v120, v119
	v_lshl_add_u64 v[116:117], v[116:117], 2, s[0:1]
	global_store_dword v[116:117], v118, off

;     __device__ __forceinline__ void operator()(const f32x4 (&acc)[2][2][4][2], const Unit& u, int wr, int wc, int fr, int fq) const {
;     ...
;                     if (sq) { float s = (v0[0] * v0[0] + v0[1] * v0[1]) + (v0[2] * v0[2] + v0[3] * v0[3]) + (v1[0] * v1[0] + v1[1] * v1[1]) + (v1[2] * v1[2] + v1[3] * v1[3]);
;                         s += __shfl_xor(s, 16); s += __shfl_xor(s, 32); if (fq == 0) sq[(size_t)row * sqp] = s; }
.LBB0_385:
	v_mul_f32_e32 v108, v103, v103
	v_mul_f32_e32 v109, v105, v105
	v_fmac_f32_e32 v108, v102, v102
	v_fmac_f32_e32 v109, v104, v104
	v_add_f32_e32 v108, v108, v109
	v_mul_f32_e32 v109, v99, v99
	v_fmac_f32_e32 v109, v98, v98
	v_add_f32_e32 v108, v108, v109
	v_mul_f32_e32 v109, v101, v101
	v_fmac_f32_e32 v109, v100, v100
	v_and_b32_e32 v110, 64, v241
	v_add_f32_e32 v108, v109, v108
	v_xor_b32_e32 v109, 16, v241
	v_add_u32_e32 v110, 64, v110
	v_cmp_lt_i32_e32 vcc, v109, v110
	s_nop 1
	v_cndmask_b32_e32 v109, v241, v109, vcc
	v_lshlrev_b32_e32 v109, 2, v109
	v_mov_b32_e32 v109, v108
	s_nop 1
	v_permlane16_swap_b32_e32 v108, v109
	s_waitcnt lgkmcnt(0)
	v_add_f32_e32 v108, v108, v109
	v_xor_b32_e32 v109, 32, v241
	v_cmp_lt_i32_e32 vcc, v109, v110
	s_nop 1
	v_cndmask_b32_e32 v109, v241, v109, vcc
	v_lshlrev_b32_e32 v109, 2, v109
	v_mov_b32_e32 v109, v108
	s_nop 1
	v_permlane32_swap_b32_e32 v108, v109
	s_and_saveexec_b64 s[34:35], s[46:47]
	s_cbranch_execz .LBB0_387
	s_waitcnt lgkmcnt(0)
	v_add_f32_e32 v110, v108, v109
	v_ashrrev_i32_e32 v108, 31, v150
	v_mul_lo_u32 v111, s29, v150
	v_mul_lo_u32 v112, s28, v108
	v_mad_u64_u32 v[108:109], s[6:7], s28, v150, 0
	v_add3_u32 v109, v109, v112, v111
	v_lshl_add_u64 v[108:109], v[108:109], 2, s[0:1]
	global_store_dword v[108:109], v110, off

;     __device__ __forceinline__ void operator()(const f32x4 (&acc)[2][2][4][2], const Unit& u, int wr, int wc, int fr, int fq) const {
;     ...
;                     if (sq) { float s = (v0[0] * v0[0] + v0[1] * v0[1]) + (v0[2] * v0[2] + v0[3] * v0[3]) + (v1[0] * v1[0] + v1[1] * v1[1]) + (v1[2] * v1[2] + v1[3] * v1[3]);
;                         s += __shfl_xor(s, 16); s += __shfl_xor(s, 32); if (fq == 0) sq[(size_t)row * sqp] = s; }
.LBB0_393:
	v_mul_f32_e32 v100, v95, v95
	v_mul_f32_e32 v101, v97, v97
	v_fmac_f32_e32 v100, v94, v94
	v_fmac_f32_e32 v101, v96, v96
	v_add_f32_e32 v100, v100, v101
	v_mul_f32_e32 v101, v91, v91
	v_fmac_f32_e32 v101, v90, v90
	v_add_f32_e32 v100, v100, v101
	v_mul_f32_e32 v101, v93, v93
	v_fmac_f32_e32 v101, v92, v92
	v_and_b32_e32 v102, 64, v241
	v_add_f32_e32 v100, v101, v100
	v_xor_b32_e32 v101, 16, v241
	v_add_u32_e32 v102, 64, v102
	v_cmp_lt_i32_e32 vcc, v101, v102
	s_nop 1
	v_cndmask_b32_e32 v101, v241, v101, vcc
	v_lshlrev_b32_e32 v101, 2, v101
	v_mov_b32_e32 v101, v100
	s_nop 1
	v_permlane16_swap_b32_e32 v100, v101
	s_waitcnt lgkmcnt(0)
	v_add_f32_e32 v100, v100, v101
	v_xor_b32_e32 v101, 32, v241
	v_cmp_lt_i32_e32 vcc, v101, v102
	s_nop 1
	v_cndmask_b32_e32 v101, v241, v101, vcc
	v_lshlrev_b32_e32 v101, 2, v101
	v_mov_b32_e32 v101, v100
	s_nop 1
	v_permlane32_swap_b32_e32 v100, v101
	s_and_saveexec_b64 s[34:35], s[46:47]
	s_cbranch_execz .LBB0_395
	s_waitcnt lgkmcnt(0)
	v_add_f32_e32 v102, v100, v101
	v_mul_lo_u32 v103, s29, v148
	v_mul_lo_u32 v104, s28, v149
	v_mad_u64_u32 v[100:101], s[6:7], s28, v148, 0
	v_add3_u32 v101, v101, v104, v103
	v_lshl_add_u64 v[100:101], v[100:101], 2, s[0:1]
	global_store_dword v[100:101], v102, off

;     __device__ __forceinline__ void operator()(const f32x4 (&acc)[2][2][4][2], const Unit& u, int wr, int wc, int fr, int fq) const {
;     ...
;                     if (sq) { float s = (v0[0] * v0[0] + v0[1] * v0[1]) + (v0[2] * v0[2] + v0[3] * v0[3]) + (v1[0] * v1[0] + v1[1] * v1[1]) + (v1[2] * v1[2] + v1[3] * v1[3]);
;                         s += __shfl_xor(s, 16); s += __shfl_xor(s, 32); if (fq == 0) sq[(size_t)row * sqp] = s; }
.LBB0_401:
	v_mul_f32_e32 v93, v87, v87
	v_mul_f32_e32 v94, v89, v89
	v_fmac_f32_e32 v93, v86, v86
	v_fmac_f32_e32 v94, v88, v88
	v_add_f32_e32 v93, v93, v94
	v_mul_f32_e32 v94, v83, v83
	v_fmac_f32_e32 v94, v82, v82
	v_add_f32_e32 v93, v93, v94
	v_mul_f32_e32 v94, v85, v85
	v_fmac_f32_e32 v94, v84, v84
	v_and_b32_e32 v95, 64, v241
	v_add_f32_e32 v93, v94, v93
	v_xor_b32_e32 v94, 16, v241
	v_add_u32_e32 v95, 64, v95
	v_cmp_lt_i32_e32 vcc, v94, v95
	s_nop 1
	v_cndmask_b32_e32 v94, v241, v94, vcc
	v_lshlrev_b32_e32 v94, 2, v94
	v_mov_b32_e32 v94, v93
	s_nop 1
	v_permlane16_swap_b32_e32 v93, v94
	s_waitcnt lgkmcnt(0)
	v_add_f32_e32 v93, v93, v94
	v_xor_b32_e32 v94, 32, v241
	v_cmp_lt_i32_e32 vcc, v94, v95
	s_nop 1
	v_cndmask_b32_e32 v94, v241, v94, vcc
	v_lshlrev_b32_e32 v94, 2, v94
	v_mov_b32_e32 v94, v93
	s_nop 1
	v_permlane32_swap_b32_e32 v93, v94
	s_and_saveexec_b64 s[34:35], s[46:47]
	s_cbranch_execz .LBB0_403
	s_waitcnt lgkmcnt(0)
	v_add_f32_e32 v93, v93, v94
	v_ashrrev_i32_e32 v94, 31, v92
	v_mul_lo_u32 v96, s29, v92
	v_mul_lo_u32 v97, s28, v94
	v_mad_u64_u32 v[94:95], s[6:7], s28, v92, 0
	v_add3_u32 v95, v95, v97, v96
	v_lshl_add_u64 v[94:95], v[94:95], 2, s[0:1]
	global_store_dword v[94:95], v93, off

;     __device__ __forceinline__ void operator()(const f32x4 (&acc)[2][2][4][2], const Unit& u, int wr, int wc, int fr, int fq) const {
;     ...
;                     if (sq) { float s = (v0[0] * v0[0] + v0[1] * v0[1]) + (v0[2] * v0[2] + v0[3] * v0[3]) + (v1[0] * v1[0] + v1[1] * v1[1]) + (v1[2] * v1[2] + v1[3] * v1[3]);
;                         s += __shfl_xor(s, 16); s += __shfl_xor(s, 32); if (fq == 0) sq[(size_t)row * sqp] = s; }
.LBB0_409:
	v_mul_f32_e32 v85, v79, v79
	v_mul_f32_e32 v86, v81, v81
	v_fmac_f32_e32 v85, v78, v78
	v_fmac_f32_e32 v86, v80, v80
	v_add_f32_e32 v85, v85, v86
	v_mul_f32_e32 v86, v75, v75
	v_fmac_f32_e32 v86, v74, v74
	v_add_f32_e32 v85, v85, v86
	v_mul_f32_e32 v86, v77, v77
	v_fmac_f32_e32 v86, v76, v76
	v_and_b32_e32 v87, 64, v241
	v_add_f32_e32 v85, v86, v85
	v_xor_b32_e32 v86, 16, v241
	v_add_u32_e32 v87, 64, v87
	v_cmp_lt_i32_e32 vcc, v86, v87
	s_nop 1
	v_cndmask_b32_e32 v86, v241, v86, vcc
	v_lshlrev_b32_e32 v86, 2, v86
	v_mov_b32_e32 v86, v85
	s_nop 1
	v_permlane16_swap_b32_e32 v85, v86
	s_waitcnt lgkmcnt(0)
	v_add_f32_e32 v85, v85, v86
	v_xor_b32_e32 v86, 32, v241
	v_cmp_lt_i32_e32 vcc, v86, v87
	s_nop 1
	v_cndmask_b32_e32 v86, v241, v86, vcc
	v_lshlrev_b32_e32 v86, 2, v86
	v_mov_b32_e32 v86, v85
	s_nop 1
	v_permlane32_swap_b32_e32 v85, v86
	s_and_saveexec_b64 s[34:35], s[46:47]
	s_cbranch_execz .LBB0_411
	s_waitcnt lgkmcnt(0)
	v_add_f32_e32 v85, v85, v86
	v_ashrrev_i32_e32 v86, 31, v84
	v_mul_lo_u32 v88, s29, v84
	v_mul_lo_u32 v89, s28, v86
	v_mad_u64_u32 v[86:87], s[6:7], s28, v84, 0
	v_add3_u32 v87, v87, v89, v88
	v_lshl_add_u64 v[86:87], v[86:87], 2, s[0:1]
	global_store_dword v[86:87], v85, off

;     __device__ __forceinline__ void operator()(const f32x4 (&acc)[2][2][4][2], const Unit& u, int wr, int wc, int fr, int fq) const {
;     ...
;                     if (sq) { float s = (v0[0] * v0[0] + v0[1] * v0[1]) + (v0[2] * v0[2] + v0[3] * v0[3]) + (v1[0] * v1[0] + v1[1] * v1[1]) + (v1[2] * v1[2] + v1[3] * v1[3]);
;                         s += __shfl_xor(s, 16); s += __shfl_xor(s, 32); if (fq == 0) sq[(size_t)row * sqp] = s; }
.LBB0_417:
	v_mul_f32_e32 v77, v71, v71
	v_mul_f32_e32 v78, v73, v73
	v_fmac_f32_e32 v77, v70, v70
	v_fmac_f32_e32 v78, v72, v72
	v_add_f32_e32 v77, v77, v78
	v_mul_f32_e32 v78, v67, v67
	v_fmac_f32_e32 v78, v66, v66
	v_add_f32_e32 v77, v77, v78
	v_mul_f32_e32 v78, v69, v69
	v_fmac_f32_e32 v78, v68, v68
	v_and_b32_e32 v79, 64, v241
	v_add_f32_e32 v77, v78, v77
	v_xor_b32_e32 v78, 16, v241
	v_add_u32_e32 v79, 64, v79
	v_cmp_lt_i32_e32 vcc, v78, v79
	s_nop 1
	v_cndmask_b32_e32 v78, v241, v78, vcc
	v_lshlrev_b32_e32 v78, 2, v78
	v_mov_b32_e32 v78, v77
	s_nop 1
	v_permlane16_swap_b32_e32 v77, v78
	s_waitcnt lgkmcnt(0)
	v_add_f32_e32 v77, v77, v78
	v_xor_b32_e32 v78, 32, v241
	v_cmp_lt_i32_e32 vcc, v78, v79
	s_nop 1
	v_cndmask_b32_e32 v78, v241, v78, vcc
	v_lshlrev_b32_e32 v78, 2, v78
	v_mov_b32_e32 v78, v77
	s_nop 1
	v_permlane32_swap_b32_e32 v77, v78
	s_and_saveexec_b64 s[34:35], s[46:47]
	s_cbranch_execz .LBB0_419
	s_waitcnt lgkmcnt(0)
	v_add_f32_e32 v77, v77, v78
	v_ashrrev_i32_e32 v78, 31, v76
	v_mul_lo_u32 v80, s29, v76
	v_mul_lo_u32 v81, s28, v78
	v_mad_u64_u32 v[78:79], s[6:7], s28, v76, 0
	v_add3_u32 v79, v79, v81, v80
	v_lshl_add_u64 v[78:79], v[78:79], 2, s[0:1]
	global_store_dword v[78:79], v77, off

;     __device__ __forceinline__ void operator()(const f32x4 (&acc)[2][2][4][2], const Unit& u, int wr, int wc, int fr, int fq) const {
;     ...
;                     if (sq) { float s = (v0[0] * v0[0] + v0[1] * v0[1]) + (v0[2] * v0[2] + v0[3] * v0[3]) + (v1[0] * v1[0] + v1[1] * v1[1]) + (v1[2] * v1[2] + v1[3] * v1[3]);
;                         s += __shfl_xor(s, 16); s += __shfl_xor(s, 32); if (fq == 0) sq[(size_t)row * sqp] = s; }
.LBB0_436:
	v_mul_f32_e32 v69, v63, v63
	v_mul_f32_e32 v70, v65, v65
	v_fmac_f32_e32 v69, v62, v62
	v_fmac_f32_e32 v70, v64, v64
	v_add_f32_e32 v69, v69, v70
	v_mul_f32_e32 v70, v59, v59
	v_fmac_f32_e32 v70, v58, v58
	v_add_f32_e32 v69, v69, v70
	v_mul_f32_e32 v70, v61, v61
	v_fmac_f32_e32 v70, v60, v60
	v_and_b32_e32 v71, 64, v241
	v_add_f32_e32 v69, v70, v69
	v_xor_b32_e32 v70, 16, v241
	v_add_u32_e32 v71, 64, v71
	v_cmp_lt_i32_e32 vcc, v70, v71
	s_nop 1
	v_cndmask_b32_e32 v70, v241, v70, vcc
	v_lshlrev_b32_e32 v70, 2, v70
	v_mov_b32_e32 v70, v69
	s_nop 1
	v_permlane16_swap_b32_e32 v69, v70
	s_waitcnt lgkmcnt(0)
	v_add_f32_e32 v69, v69, v70
	v_xor_b32_e32 v70, 32, v241
	v_cmp_lt_i32_e32 vcc, v70, v71
	s_nop 1
	v_cndmask_b32_e32 v70, v241, v70, vcc
	v_lshlrev_b32_e32 v70, 2, v70
	v_mov_b32_e32 v70, v69
	s_nop 1
	v_permlane32_swap_b32_e32 v69, v70
	s_and_saveexec_b64 s[30:31], s[46:47]
	s_cbranch_execz .LBB0_438
	s_waitcnt lgkmcnt(0)
	v_add_f32_e32 v69, v69, v70
	v_mul_lo_u32 v72, s29, v156
	v_mul_lo_u32 v73, s28, v157
	v_mad_u64_u32 v[70:71], s[6:7], s28, v156, 0
	v_add3_u32 v71, v71, v73, v72
	v_lshl_add_u64 v[70:71], v[70:71], 2, s[0:1]
	global_store_dword v[70:71], v69, off

;     __device__ __forceinline__ void operator()(const f32x4 (&acc)[2][2][4][2], const Unit& u, int wr, int wc, int fr, int fq) const {
;     ...
;                     if (sq) { float s = (v0[0] * v0[0] + v0[1] * v0[1]) + (v0[2] * v0[2] + v0[3] * v0[3]) + (v1[0] * v1[0] + v1[1] * v1[1]) + (v1[2] * v1[2] + v1[3] * v1[3]);
;                         s += __shfl_xor(s, 16); s += __shfl_xor(s, 32); if (fq == 0) sq[(size_t)row * sqp] = s; }
.LBB0_444:
	v_mul_f32_e32 v58, v55, v55
	v_mul_f32_e32 v59, v57, v57
	v_fmac_f32_e32 v58, v54, v54
	v_fmac_f32_e32 v59, v56, v56
	v_add_f32_e32 v58, v58, v59
	v_mul_f32_e32 v59, v51, v51
	v_fmac_f32_e32 v59, v50, v50
	v_add_f32_e32 v58, v58, v59
	v_mul_f32_e32 v59, v53, v53
	v_fmac_f32_e32 v59, v52, v52
	v_and_b32_e32 v60, 64, v241
	v_add_f32_e32 v58, v59, v58
	v_xor_b32_e32 v59, 16, v241
	v_add_u32_e32 v60, 64, v60
	v_cmp_lt_i32_e32 vcc, v59, v60
	s_nop 1
	v_cndmask_b32_e32 v59, v241, v59, vcc
	v_lshlrev_b32_e32 v59, 2, v59
	v_mov_b32_e32 v59, v58
	s_nop 1
	v_permlane16_swap_b32_e32 v58, v59
	s_waitcnt lgkmcnt(0)
	v_add_f32_e32 v58, v58, v59
	v_xor_b32_e32 v59, 32, v241
	v_cmp_lt_i32_e32 vcc, v59, v60
	s_nop 1
	v_cndmask_b32_e32 v59, v241, v59, vcc
	v_lshlrev_b32_e32 v59, 2, v59
	v_mov_b32_e32 v59, v58
	s_nop 1
	v_permlane32_swap_b32_e32 v58, v59
	s_and_saveexec_b64 s[34:35], s[46:47]
	s_cbranch_execz .LBB0_446
	v_ashrrev_i32_e32 v60, 31, v154
	s_waitcnt lgkmcnt(0)
	v_add_f32_e32 v61, v58, v59
	v_mul_lo_u32 v62, s29, v154
	v_mul_lo_u32 v60, s28, v60
	v_mad_u64_u32 v[58:59], s[6:7], s28, v154, 0
	v_add3_u32 v59, v59, v60, v62
	v_lshl_add_u64 v[58:59], v[58:59], 2, s[0:1]
	global_store_dword v[58:59], v61, off

;     __device__ __forceinline__ void operator()(const f32x4 (&acc)[2][2][4][2], const Unit& u, int wr, int wc, int fr, int fq) const {
;     ...
;                     if (sq) { float s = (v0[0] * v0[0] + v0[1] * v0[1]) + (v0[2] * v0[2] + v0[3] * v0[3]) + (v1[0] * v1[0] + v1[1] * v1[1]) + (v1[2] * v1[2] + v1[3] * v1[3]);
;                         s += __shfl_xor(s, 16); s += __shfl_xor(s, 32); if (fq == 0) sq[(size_t)row * sqp] = s; }
.LBB0_452:
	v_mul_f32_e32 v50, v47, v47
	v_mul_f32_e32 v51, v49, v49
	v_fmac_f32_e32 v50, v46, v46
	v_fmac_f32_e32 v51, v48, v48
	v_add_f32_e32 v50, v50, v51
	v_mul_f32_e32 v51, v43, v43
	v_fmac_f32_e32 v51, v42, v42
	v_add_f32_e32 v50, v50, v51
	v_mul_f32_e32 v51, v45, v45
	v_fmac_f32_e32 v51, v44, v44
	v_and_b32_e32 v52, 64, v241
	v_add_f32_e32 v50, v51, v50
	v_xor_b32_e32 v51, 16, v241
	v_add_u32_e32 v52, 64, v52
	v_cmp_lt_i32_e32 vcc, v51, v52
	s_nop 1
	v_cndmask_b32_e32 v51, v241, v51, vcc
	v_lshlrev_b32_e32 v51, 2, v51
	v_mov_b32_e32 v51, v50
	s_nop 1
	v_permlane16_swap_b32_e32 v50, v51
	s_waitcnt lgkmcnt(0)
	v_add_f32_e32 v50, v50, v51
	v_xor_b32_e32 v51, 32, v241
	v_cmp_lt_i32_e32 vcc, v51, v52
	s_nop 1
	v_cndmask_b32_e32 v51, v241, v51, vcc
	v_lshlrev_b32_e32 v51, 2, v51
	v_mov_b32_e32 v51, v50
	s_nop 1
	v_permlane32_swap_b32_e32 v50, v51
	s_and_saveexec_b64 s[34:35], s[46:47]
	s_cbranch_execz .LBB0_454
	v_ashrrev_i32_e32 v52, 31, v152
	s_waitcnt lgkmcnt(0)
	v_add_f32_e32 v53, v50, v51
	v_mul_lo_u32 v54, s29, v152
	v_mul_lo_u32 v52, s28, v52
	v_mad_u64_u32 v[50:51], s[6:7], s28, v152, 0
	v_add3_u32 v51, v51, v52, v54
	v_lshl_add_u64 v[50:51], v[50:51], 2, s[0:1]
	global_store_dword v[50:51], v53, off

;     __device__ __forceinline__ void operator()(const f32x4 (&acc)[2][2][4][2], const Unit& u, int wr, int wc, int fr, int fq) const {
;     ...
;                     if (sq) { float s = (v0[0] * v0[0] + v0[1] * v0[1]) + (v0[2] * v0[2] + v0[3] * v0[3]) + (v1[0] * v1[0] + v1[1] * v1[1]) + (v1[2] * v1[2] + v1[3] * v1[3]);
;                         s += __shfl_xor(s, 16); s += __shfl_xor(s, 32); if (fq == 0) sq[(size_t)row * sqp] = s; }
.LBB0_460:
	v_mul_f32_e32 v42, v39, v39
	v_mul_f32_e32 v43, v41, v41
	v_fmac_f32_e32 v42, v38, v38
	v_fmac_f32_e32 v43, v40, v40
	v_add_f32_e32 v42, v42, v43
	v_mul_f32_e32 v43, v35, v35
	v_fmac_f32_e32 v43, v34, v34
	v_add_f32_e32 v42, v42, v43
	v_mul_f32_e32 v43, v37, v37
	v_fmac_f32_e32 v43, v36, v36
	v_and_b32_e32 v44, 64, v241
	v_add_f32_e32 v42, v43, v42
	v_xor_b32_e32 v43, 16, v241
	v_add_u32_e32 v44, 64, v44
	v_cmp_lt_i32_e32 vcc, v43, v44
	s_nop 1
	v_cndmask_b32_e32 v43, v241, v43, vcc
	v_lshlrev_b32_e32 v43, 2, v43
	v_mov_b32_e32 v43, v42
	s_nop 1
	v_permlane16_swap_b32_e32 v42, v43
	s_waitcnt lgkmcnt(0)
	v_add_f32_e32 v42, v42, v43
	v_xor_b32_e32 v43, 32, v241
	v_cmp_lt_i32_e32 vcc, v43, v44
	s_nop 1
	v_cndmask_b32_e32 v43, v241, v43, vcc
	v_lshlrev_b32_e32 v43, 2, v43
	v_mov_b32_e32 v43, v42
	s_nop 1
	v_permlane32_swap_b32_e32 v42, v43
	s_and_saveexec_b64 s[34:35], s[46:47]
	s_cbranch_execz .LBB0_462
	v_ashrrev_i32_e32 v44, 31, v150
	s_waitcnt lgkmcnt(0)
	v_add_f32_e32 v45, v42, v43
	v_mul_lo_u32 v46, s29, v150
	v_mul_lo_u32 v44, s28, v44
	v_mad_u64_u32 v[42:43], s[6:7], s28, v150, 0
	v_add3_u32 v43, v43, v44, v46
	v_lshl_add_u64 v[42:43], v[42:43], 2, s[0:1]
	global_store_dword v[42:43], v45, off

;     __device__ __forceinline__ void operator()(const f32x4 (&acc)[2][2][4][2], const Unit& u, int wr, int wc, int fr, int fq) const {
;     ...
;                     if (sq) { float s = (v0[0] * v0[0] + v0[1] * v0[1]) + (v0[2] * v0[2] + v0[3] * v0[3]) + (v1[0] * v1[0] + v1[1] * v1[1]) + (v1[2] * v1[2] + v1[3] * v1[3]);
;                         s += __shfl_xor(s, 16); s += __shfl_xor(s, 32); if (fq == 0) sq[(size_t)row * sqp] = s; }
.LBB0_468:
	v_mul_f32_e32 v34, v31, v31
	v_mul_f32_e32 v35, v33, v33
	v_fmac_f32_e32 v34, v30, v30
	v_fmac_f32_e32 v35, v32, v32
	v_add_f32_e32 v34, v34, v35
	v_mul_f32_e32 v35, v27, v27
	v_fmac_f32_e32 v35, v26, v26
	v_add_f32_e32 v34, v34, v35
	v_mul_f32_e32 v35, v29, v29
	v_fmac_f32_e32 v35, v28, v28
	v_and_b32_e32 v36, 64, v241
	v_add_f32_e32 v34, v35, v34
	v_xor_b32_e32 v35, 16, v241
	v_add_u32_e32 v36, 64, v36
	v_cmp_lt_i32_e32 vcc, v35, v36
	s_nop 1
	v_cndmask_b32_e32 v35, v241, v35, vcc
	v_lshlrev_b32_e32 v35, 2, v35
	v_mov_b32_e32 v35, v34
	s_nop 1
	v_permlane16_swap_b32_e32 v34, v35
	s_waitcnt lgkmcnt(0)
	v_add_f32_e32 v34, v34, v35
	v_xor_b32_e32 v35, 32, v241
	v_cmp_lt_i32_e32 vcc, v35, v36
	s_nop 1
	v_cndmask_b32_e32 v35, v241, v35, vcc
	v_lshlrev_b32_e32 v35, 2, v35
	v_mov_b32_e32 v35, v34
	s_nop 1
	v_permlane32_swap_b32_e32 v34, v35
	s_and_saveexec_b64 s[34:35], s[46:47]
	s_cbranch_execz .LBB0_470
	s_waitcnt lgkmcnt(0)
	v_add_f32_e32 v36, v34, v35
	v_mul_lo_u32 v37, s29, v148
	v_mul_lo_u32 v38, s28, v149
	v_mad_u64_u32 v[34:35], s[6:7], s28, v148, 0
	v_add3_u32 v35, v35, v38, v37
	v_lshl_add_u64 v[34:35], v[34:35], 2, s[0:1]
	global_store_dword v[34:35], v36, off

;     __device__ __forceinline__ void operator()(const f32x4 (&acc)[2][2][4][2], const Unit& u, int wr, int wc, int fr, int fq) const {
;     ...
;                     if (sq) { float s = (v0[0] * v0[0] + v0[1] * v0[1]) + (v0[2] * v0[2] + v0[3] * v0[3]) + (v1[0] * v1[0] + v1[1] * v1[1]) + (v1[2] * v1[2] + v1[3] * v1[3]);
;                         s += __shfl_xor(s, 16); s += __shfl_xor(s, 32); if (fq == 0) sq[(size_t)row * sqp] = s; }
.LBB0_476:
	v_mul_f32_e32 v26, v23, v23
	v_mul_f32_e32 v27, v25, v25
	v_fmac_f32_e32 v26, v22, v22
	v_fmac_f32_e32 v27, v24, v24
	v_add_f32_e32 v26, v26, v27
	v_mul_f32_e32 v27, v19, v19
	v_fmac_f32_e32 v27, v18, v18
	v_add_f32_e32 v26, v26, v27
	v_mul_f32_e32 v27, v21, v21
	v_fmac_f32_e32 v27, v20, v20
	v_and_b32_e32 v28, 64, v241
	v_add_f32_e32 v26, v27, v26
	v_xor_b32_e32 v27, 16, v241
	v_add_u32_e32 v28, 64, v28
	v_cmp_lt_i32_e32 vcc, v27, v28
	s_nop 1
	v_cndmask_b32_e32 v27, v241, v27, vcc
	v_lshlrev_b32_e32 v27, 2, v27
	v_mov_b32_e32 v27, v26
	s_nop 1
	v_permlane16_swap_b32_e32 v26, v27
	s_waitcnt lgkmcnt(0)
	v_add_f32_e32 v26, v26, v27
	v_xor_b32_e32 v27, 32, v241
	v_cmp_lt_i32_e32 vcc, v27, v28
	s_nop 1
	v_cndmask_b32_e32 v27, v241, v27, vcc
	v_lshlrev_b32_e32 v27, 2, v27
	v_mov_b32_e32 v27, v26
	s_nop 1
	v_permlane32_swap_b32_e32 v26, v27
	s_and_saveexec_b64 s[34:35], s[46:47]
	s_cbranch_execz .LBB0_478
	v_ashrrev_i32_e32 v28, 31, v92
	s_waitcnt lgkmcnt(0)
	v_add_f32_e32 v29, v26, v27
	v_mul_lo_u32 v30, s29, v92
	v_mul_lo_u32 v28, s28, v28
	v_mad_u64_u32 v[26:27], s[6:7], s28, v92, 0
	v_add3_u32 v27, v27, v28, v30
	v_lshl_add_u64 v[26:27], v[26:27], 2, s[0:1]
	global_store_dword v[26:27], v29, off

;     __device__ __forceinline__ void operator()(const f32x4 (&acc)[2][2][4][2], const Unit& u, int wr, int wc, int fr, int fq) const {
;     ...
;                     if (sq) { float s = (v0[0] * v0[0] + v0[1] * v0[1]) + (v0[2] * v0[2] + v0[3] * v0[3]) + (v1[0] * v1[0] + v1[1] * v1[1]) + (v1[2] * v1[2] + v1[3] * v1[3]);
;                         s += __shfl_xor(s, 16); s += __shfl_xor(s, 32); if (fq == 0) sq[(size_t)row * sqp] = s; }
.LBB0_484:
	v_mul_f32_e32 v18, v15, v15
	v_mul_f32_e32 v19, v17, v17
	v_fmac_f32_e32 v18, v14, v14
	v_fmac_f32_e32 v19, v16, v16
	v_add_f32_e32 v18, v18, v19
	v_mul_f32_e32 v19, v11, v11
	v_fmac_f32_e32 v19, v10, v10
	v_add_f32_e32 v18, v18, v19
	v_mul_f32_e32 v19, v13, v13
	v_fmac_f32_e32 v19, v12, v12
	v_and_b32_e32 v20, 64, v241
	v_add_f32_e32 v18, v19, v18
	v_xor_b32_e32 v19, 16, v241
	v_add_u32_e32 v20, 64, v20
	v_cmp_lt_i32_e32 vcc, v19, v20
	s_nop 1
	v_cndmask_b32_e32 v19, v241, v19, vcc
	v_lshlrev_b32_e32 v19, 2, v19
	v_mov_b32_e32 v19, v18
	s_nop 1
	v_permlane16_swap_b32_e32 v18, v19
	s_waitcnt lgkmcnt(0)
	v_add_f32_e32 v18, v18, v19
	v_xor_b32_e32 v19, 32, v241
	v_cmp_lt_i32_e32 vcc, v19, v20
	s_nop 1
	v_cndmask_b32_e32 v19, v241, v19, vcc
	v_lshlrev_b32_e32 v19, 2, v19
	v_mov_b32_e32 v19, v18
	s_nop 1
	v_permlane32_swap_b32_e32 v18, v19
	s_and_saveexec_b64 s[34:35], s[46:47]
	s_cbranch_execz .LBB0_486
	v_ashrrev_i32_e32 v20, 31, v84
	s_waitcnt lgkmcnt(0)
	v_add_f32_e32 v21, v18, v19
	v_mul_lo_u32 v22, s29, v84
	v_mul_lo_u32 v20, s28, v20
	v_mad_u64_u32 v[18:19], s[6:7], s28, v84, 0
	v_add3_u32 v19, v19, v20, v22
	v_lshl_add_u64 v[18:19], v[18:19], 2, s[0:1]
	global_store_dword v[18:19], v21, off

;     __device__ __forceinline__ void operator()(const f32x4 (&acc)[2][2][4][2], const Unit& u, int wr, int wc, int fr, int fq) const {
;     ...
;                     if (sq) { float s = (v0[0] * v0[0] + v0[1] * v0[1]) + (v0[2] * v0[2] + v0[3] * v0[3]) + (v1[0] * v1[0] + v1[1] * v1[1]) + (v1[2] * v1[2] + v1[3] * v1[3]);
;                         s += __shfl_xor(s, 16); s += __shfl_xor(s, 32); if (fq == 0) sq[(size_t)row * sqp] = s; }
.LBB0_491:
	v_readlane_b32 s50, v254, 18
	v_readlane_b32 s51, v254, 19
	s_and_b64 vcc, exec, s[54:55]
	s_mov_b32 s55, 0x800000
	s_cbranch_vccnz .LBB0_495
	v_mul_f32_e32 v10, v7, v7
	v_mul_f32_e32 v11, v9, v9
	v_fmac_f32_e32 v10, v6, v6
	v_fmac_f32_e32 v11, v8, v8
	v_add_f32_e32 v10, v10, v11
	v_mul_f32_e32 v11, v3, v3
	v_fmac_f32_e32 v11, v2, v2
	v_add_f32_e32 v10, v10, v11
	v_mul_f32_e32 v11, v5, v5
	v_fmac_f32_e32 v11, v4, v4
	v_and_b32_e32 v12, 64, v241
	v_add_f32_e32 v10, v11, v10
	v_xor_b32_e32 v11, 16, v241
	v_add_u32_e32 v12, 64, v12
	v_cmp_lt_i32_e32 vcc, v11, v12
	s_nop 1
	v_cndmask_b32_e32 v11, v241, v11, vcc
	v_lshlrev_b32_e32 v11, 2, v11
	v_mov_b32_e32 v11, v10
	s_nop 1
	v_permlane16_swap_b32_e32 v10, v11
	s_waitcnt lgkmcnt(0)
	v_add_f32_e32 v10, v10, v11
	v_xor_b32_e32 v11, 32, v241
	v_cmp_lt_i32_e32 vcc, v11, v12
	s_nop 1
	v_cndmask_b32_e32 v11, v241, v11, vcc
	v_lshlrev_b32_e32 v11, 2, v11
	v_mov_b32_e32 v11, v10
	s_nop 1
	v_permlane32_swap_b32_e32 v10, v11
	s_and_saveexec_b64 s[34:35], s[46:47]
	s_cbranch_execz .LBB0_494
	v_ashrrev_i32_e32 v12, 31, v76
	s_waitcnt lgkmcnt(0)
	v_add_f32_e32 v13, v10, v11
	v_mul_lo_u32 v14, s29, v76
	v_mul_lo_u32 v12, s28, v12
	v_mad_u64_u32 v[10:11], s[6:7], s28, v76, 0
	v_add3_u32 v11, v11, v12, v14
	v_lshl_add_u64 v[10:11], v[10:11], 2, s[0:1]
	global_store_dword v[10:11], v13, off
